# v9 plus K tile rows permuted at LDS-DMA time so the fp8 P fragments need no v_permlane32_swap before the PV MFMAs
# speedup vs baseline: 1.0142x; 1.0106x over previous
; #define LAS __attribute__((address_space(3)))
; __device__ __forceinline__ int lane_id() { return (int)__builtin_amdgcn_mbcnt_hi(~0u, __builtin_amdgcn_mbcnt_lo(~0u, 0u)); }
; #define lane lane_id()
; __device__ __forceinline__ void body(const unsigned char* Q8b, const unsigned char* K8h, const unsigned char* VT8h, const bf16_t* Gb, bf16_t* Ob, int seq, char* lds, const int wid, ...
;   const int lane = lane_id(), tid = wid * 64 + lane, r32 = lane & 31, hi = lane >> 5;
;   char* V_lds = lds; char* K_lds = lds + K_OFF;
;   float* ws = (float*)(lds + WS_OFF) + wid * 64; float* al_l = ws + 32;
;   f32x16 o[4] = {}; f32x16 ls = {}; f32x16 nm;
; #pragma unroll
;   for (int r = 0; r < 16; ++r) nm[r] = PSHIFT;
;   LAS char* L3 = (LAS char*)lds;
;   const int krow = wid * 8 + (lane >> 3), kc = (lane & 7) ^ ((krow >> 1) & 7);
;   const char* Kg = (const char*)K8h + krow * 256 + kc * 16; const char* Vg = (const char*)VT8h + wid * 1024 + lane * 16;
;   const int ksw = (r32 >> 1) & 7, ko = r32 * 128, c00 = ((0 + hi * 2) ^ ksw) << 4, c01 = ((1 + hi * 2) ^ ksw) << 4, c10 = ((4 + hi * 2) ^ ksw) << 4, c11 = ((5 + hi * 2) ^ ksw) << 4;
;   const int vsw = (r32 >> 2) & 3, vo = r32 * 64, e0 = ((2 * hi) ^ vsw) << 4, e1 = ((2 * hi + 1) ^ vsw) << 4;
.LBB0_357:
	s_and_b64 vcc, exec, s[4:5]
	s_cbranch_vccnz .LBB0_393
	v_mbcnt_lo_u32_b32 v0, -1, 0
	v_mbcnt_hi_u32_b32 v1, -1, v0
	s_and_b32 s4, s2, 7
	v_lshrrev_b32_e32 v9, 5, v1
	s_mul_i32 s4, s4, 10
	v_bfe_u32 v5, v1, 1, 3
	v_lshlrev_b32_e32 v6, 1, v9
	s_or_b32 s29, s4, 1
	s_ashr_i32 s31, s2, 3
	v_bitop3_b32 v5, v6, v5, 1 bitop3:0x36
	s_waitcnt lgkmcnt(0)
	s_add_u32 s63, s8, 0xc000000
	v_lshrrev_b32_e32 v4, 1, v1
	v_lshlrev_b32_e32 v229, 4, v5
	v_add_u32_e32 v5, 4, v6
	s_addc_u32 s64, s9, 0
	v_lshrrev_b32_e32 v0, 3, v1
	v_bitop3_b32 v5, v5, v4, 7 bitop3:0x78
	s_add_u32 s65, s8, 0x16000000
	v_lshl_add_u32 v0, s33, 3, v0
	v_lshlrev_b32_e32 v230, 4, v5
	v_add_u32_e32 v5, 5, v6
	s_addc_u32 s66, s9, 0
	s_lshl_b32 s4, s33, 8
	v_lshrrev_b32_e32 v2, 1, v0
	v_bitop3_b32 v7, v6, v4, 7 bitop3:0x78
	v_bitop3_b32 v4, v5, v4, 7 bitop3:0x78
	s_add_i32 s67, s4, 0
	v_xor_b32_e32 v2, v2, v1
	v_lshlrev_b32_e32 v231, 4, v4
	v_lshrrev_b32_e32 v4, 2, v1
	s_add_i32 s67, s67, 0x10000
	v_lshrrev_b32_e32 v254, 2, v0
	v_lshrrev_b32_e32 v255, 5, v0
	v_xor_b32_e32 v254, v254, v255
	v_and_b32_e32 v254, 1, v254
	v_mul_u32_u24_e32 v254, 36, v254
	v_xor_b32_e32 v254, v254, v0
	v_lshlrev_b32_e32 v202, 8, v254
	v_lshlrev_b32_e32 v0, 4, v2
	s_lshl_b32 s10, s33, 10
	v_bfe_u32 v5, v1, 2, 2
	v_bitop3_b32 v4, v6, v4, 3 bitop3:0x78
	v_and_b32_e32 v8, 31, v1
	v_and_b32_e32 v204, 0x70, v0
	v_mov_b32_e32 v0, 0
	s_add_u32 s4, s8, s10
	v_lshlrev_b32_e32 v232, 4, v4
	v_bitop3_b32 v4, v6, v5, 1 bitop3:0x36
	v_lshlrev_b32_e32 v2, 4, v1
	v_mov_b32_e32 v3, v0
	s_addc_u32 s5, s9, 0
	v_lshlrev_b32_e32 v233, 4, v4
	s_add_i32 s68, s10, 0
	v_lshl_add_u32 v234, v8, 7, 0
	v_lshlrev_b32_e32 v4, 6, v8
	s_lshl_b32 s10, s33, 15
	v_lshrrev_b32_e32 v10, 4, v1
	v_lshl_add_u64 v[2:3], s[4:5], 0, v[2:3]
	s_mov_b64 s[4:5], 0x18800000
	v_sub_u32_e32 v235, v234, v4
	v_lshl_or_b32 v4, v10, 10, s10
	v_lshl_add_u64 v[206:207], v[2:3], 0, s[4:5]
	v_cmp_gt_u32_e64 s[4:5], 32, v1
	v_and_b32_e32 v210, 0x60, v1
	v_and_b32_e32 v1, 15, v1
	v_ashrrev_i32_e32 v5, 31, v4
	v_lshlrev_b32_e32 v228, 4, v7
	v_lshlrev_b32_e32 v6, 4, v1
	v_mov_b32_e32 v7, v0
	v_lshl_add_u64 v[4:5], v[4:5], 1, s[8:9]
	v_lshl_or_b32 v208, v8, 10, s10
	v_lshl_add_u64 v[4:5], v[4:5], 0, v[6:7]
	s_mov_b64 s[10:11], 0x1b000000
	v_lshl_add_u64 v[212:213], v[4:5], 0, s[10:11]
	s_mul_i32 s10, s33, 0x2200
	s_add_i32 s10, s10, 0
	s_add_i32 s12, s10, 0x10800
	v_lshlrev_b32_e32 v1, 1, v8
	v_mul_u32_u24_e32 v7, 0x440, v9
	s_mov_b64 s[10:11], 0x2000000
	v_add3_u32 v238, s12, v1, v7
	v_lshl_add_u64 v[214:215], v[4:5], 0, s[10:11]
	s_movk_i32 s10, 0x110
	v_mov_b32_e32 v1, s12
	v_ashrrev_i32_e32 v203, 31, v202
	v_mad_u32_u24 v1, v10, s10, v1
	s_mov_b64 s[10:11], 0x18806000
	v_lshl_add_u64 v[216:217], v[2:3], 0, s[10:11]
	v_or_b32_e32 v2, v202, v204
	v_mov_b32_e32 v3, v203
	v_lshl_add_u64 v[2:3], s[8:9], 0, v[2:3]
	s_mov_b64 s[8:9], 0x1600c000
	v_lshl_add_u64 v[218:219], v[2:3], 0, s[8:9]
	s_mov_b32 s8, 0x40a00000
	s_mov_b32 s37, 0
	v_mov_b32_e32 v205, v0
	v_lshl_add_u32 v236, v8, 2, s67
	v_lshlrev_b32_e32 v237, 4, v9
	v_ashrrev_i32_e32 v209, 31, v208
	v_mov_b32_e32 v211, v0
	s_mov_b32 s69, 0x8000
	s_add_i32 s70, s68, 0x8000
	s_mov_b64 s[38:39], 0x4000
	s_mov_b32 s71, 0xa000
	s_add_i32 s72, s68, 0xa000
	s_mov_b64 s[40:41], 0x2000
	s_movk_i32 s73, 0x2000
	s_add_i32 s74, s68, 0x2000
	s_mov_b64 s[42:43], 0x8000
	s_mov_b32 s75, 0xc000
	s_add_i32 s76, s68, 0xc000
	s_movk_i32 s77, 0x4000
	s_add_i32 s78, s68, 0x4000
	s_mov_b32 s9, s8
	s_mov_b32 s10, s8
	s_mov_b32 s11, s8
	s_mov_b32 s12, s8
	s_mov_b32 s13, s8
	s_mov_b32 s14, s8
	s_mov_b32 s15, s8
	s_mov_b32 s16, s8
	s_mov_b32 s17, s8
	s_mov_b32 s18, s8
	s_mov_b32 s19, s8
	s_mov_b32 s20, s8
	s_mov_b32 s21, s8
	s_mov_b32 s22, s8
	s_mov_b32 s23, s8
	v_mov_b32_e32 v239, 0x7c7c7c7c
	v_mov_b32_e32 v240, 0x7f7f7f7f
	s_movk_i32 s79, 0x6000
	s_mov_b32 s80, 0x40fc551e
	s_mov_b32 s81, 0xe000
	v_add_u32_e32 v241, v1, v6
	v_mov_b32_e32 v192, 0x38383838
	s_mov_b32 s82, 0
	s_lshr_b32 s92, s33, 2
	v_add_u32_e32 v242, v234, v228
	v_add_u32_e32 v243, v234, v229
	v_add_u32_e32 v244, v234, v230
	v_add_u32_e32 v245, v234, v231
	v_add_u32_e32 v254, v235, v232
	v_add_u32_e32 v255, v235, v233
	v_mov_b32_e32 v228, v192
	v_mov_b32_e32 v229, v192
	v_mov_b32_e32 v230, v192
	v_mov_b32_e32 v231, v192
	v_mov_b32_e32 v232, v192
	v_mov_b32_e32 v233, v192
	v_mov_b32_e32 v234, v192
	v_mov_b32_e32 v235, v192
	s_mov_b32 s93, 0
	s_branch .LBB0_360

; #define SBAR() __builtin_amdgcn_sched_barrier(0)
; #define MFMA8Q(A, B, C) __builtin_amdgcn_mfma_scale_f32_32x32x64_f8f6f4(A, B, C, 0, 0, 0, SCL1, 0, 0x7C7C7C7C)
; __device__ __forceinline__ v8i ld32(const char* p0, const char* p1) { const u32x4 a = *(const u32x4*)p0, b = *(const u32x4*)p1; return (v8i){(int)a.x, (int)a.y, (int)a.z, (int)a.w, (int)b.x, (int)b.y, (int)b.z, (int)b.w}; }
; #define DMA(slot, t) do { \
;     __builtin_amdgcn_global_load_lds((const unsigned*)(Kg + (long)(t) * (64 * 256)), (LAS unsigned*)(L3 + K_OFF + (slot) * SHM_T + wid * 1024), 16, 0, 0); \
;     __builtin_amdgcn_global_load_lds((const unsigned*)(Vg + (long)(t) * 8192), (LAS unsigned*)(L3 + (slot) * SHM_T + wid * 1024), 16, 0, 0); } while (0)
; #define QKT(P0, P1, b) qkt(P0, P1, nm, K_lds + (b) * SHM_T, qr, ko, c00, c01, c10, c11)
; __device__ __forceinline__ void finishSM(f32x16& p0, f32x16& p1, v8i& pf) {
;   for (int r = 0; r < 16; ++r) p1[r] = __builtin_amdgcn_exp2f(p1[r]);
; #pragma unroll
;   for (int j = 0; j < 4; ++j) {
;     int a = __builtin_amdgcn_cvt_pk_fp8_f32(p0[4 * j], p0[4 * j + 1], 0, false); a = __builtin_amdgcn_cvt_pk_fp8_f32(p0[4 * j + 2], p0[4 * j + 3], a, true);
;     int b = __builtin_amdgcn_cvt_pk_fp8_f32(p1[4 * j], p1[4 * j + 1], 0, false); b = __builtin_amdgcn_cvt_pk_fp8_f32(p1[4 * j + 2], p1[4 * j + 3], b, true);
;     auto rr = __builtin_amdgcn_permlane32_swap((unsigned)a, (unsigned)b, false, false);
;     pf[2 * j] = (int)rr[0]; pf[2 * j + 1] = (int)rr[1]; }
; }
; __device__ __forceinline__ void qkt(f32x16& p0, f32x16& p1, const f32x16& nm, const char* Ks, const v8i* qr, int ko, int c00, int c01, int c10, int c11) {
;   { const v8i a0 = ld32(Ks + ko + c00, Ks + ko + c01), a1 = ld32(Ks + 4096 + ko + c00, Ks + 4096 + ko + c01);
;     p0 = MFMA8Q(a0, qr[0], nm); p1 = MFMA8Q(a1, qr[0], nm); }
;   { const v8i a0 = ld32(Ks + ko + c10, Ks + ko + c11), a1 = ld32(Ks + 4096 + ko + c10, Ks + 4096 + ko + c11);
;     p0 = MFMA8Q(a0, qr[1], p0); p1 = MFMA8Q(a1, qr[1], p1); }
; }
; __device__ __forceinline__ void body(const unsigned char* Q8b, const unsigned char* K8h, const unsigned char* VT8h, const bf16_t* Gb, bf16_t* Ob, int seq, char* lds, const int wid, ...
;     ...
;     SBAR(); QKT(pB0, pB1, (s0 + 1) & 3);
;     finishSM(pA0, pA1, pf); PIPE1(); SBAR();
;     DMA((s0 + 3) & 3, i + 3);
;     SBAR();
;     HALF2(pB0, pB1, alB, s0);
.LBB0_374:
	ds_read_b128 v[2:5], v242 offset:40960
	ds_read_b128 v[6:9], v243 offset:40960
	ds_read_b128 v[128:131], v242 offset:45056
	ds_read_b128 v[132:135], v243 offset:45056
	ds_read_b128 v[194:197], v244 offset:40960
	ds_read_b128 v[198:201], v245 offset:40960
	ds_read_b128 v[246:249], v244 offset:45056
	ds_read_b128 v[250:253], v245 offset:45056
	v_exp_f32_e32 v1, v112
	v_exp_f32_e32 v10, v113
	v_exp_f32_e32 v11, v114
	v_exp_f32_e32 v12, v115
	s_waitcnt lgkmcnt(6)
	s_setprio 1
	v_mfma_scale_f32_32x32x64_f8f6f4 v[160:175], v[2:9], v[176:183], v[96:111], v240, v239 op_sel_hi:[0,0,0]
	v_exp_f32_e32 v6, v116
	v_exp_f32_e32 v7, v117
	v_exp_f32_e32 v8, v118
	v_exp_f32_e32 v9, v119
	v_cvt_pk_fp8_f32 v5, v6, v7
	v_cvt_pk_fp8_f32 v3, v1, v10
	v_cvt_pk_fp8_f32 v5, v8, v9 op_sel:[0,0,1]
	s_waitcnt lgkmcnt(4)
	v_mfma_scale_f32_32x32x64_f8f6f4 v[128:143], v[128:135], v[176:183], v[96:111], v240, v239 op_sel_hi:[0,0,0]
	v_exp_f32_e32 v13, v120
	v_exp_f32_e32 v14, v121
	v_exp_f32_e32 v15, v122
	v_exp_f32_e32 v112, v123
	v_cvt_pk_fp8_f32 v2, v144, v145
	v_cvt_pk_fp8_f32 v4, v148, v149
	v_cvt_pk_fp8_f32 v6, v152, v153
	v_cvt_pk_fp8_f32 v7, v13, v14
	v_cvt_pk_fp8_f32 v8, v156, v157
	v_cvt_pk_fp8_f32 v2, v146, v147 op_sel:[0,0,1]
	v_cvt_pk_fp8_f32 v3, v11, v12 op_sel:[0,0,1]
	v_cvt_pk_fp8_f32 v4, v150, v151 op_sel:[0,0,1]
	v_cvt_pk_fp8_f32 v6, v154, v155 op_sel:[0,0,1]
	v_cvt_pk_fp8_f32 v7, v15, v112 op_sel:[0,0,1]
	v_cvt_pk_fp8_f32 v8, v158, v159 op_sel:[0,0,1]
	s_waitcnt lgkmcnt(2)
	v_mfma_scale_f32_32x32x64_f8f6f4 v[160:175], v[194:201], v[184:191], v[160:175], v240, v239 op_sel_hi:[0,0,0]
	v_exp_f32_e32 v113, v124
	v_exp_f32_e32 v114, v125
	v_exp_f32_e32 v1, v126
	v_exp_f32_e32 v10, v127
	v_cvt_pk_fp8_f32 v9, v113, v114
	s_nop 0
	v_cvt_pk_fp8_f32 v9, v1, v10 op_sel:[0,0,1]
	s_waitcnt lgkmcnt(0)
	v_mfma_scale_f32_32x32x64_f8f6f4 v[128:143], v[246:253], v[184:191], v[128:143], v240, v239 op_sel_hi:[0,0,0]
	s_setprio 0
	s_add_i32 m0, s68, 0xe000
	s_nop 0
	global_load_lds_dwordx4 v192, s[98:99]
	s_add_i32 m0, s68, 0x6000
	s_nop 0
	global_load_lds_dwordx4 v193, s[100:101]
	ds_read_b128 v[194:197], v254
	ds_read_b128 v[148:151], v254 offset:2048
	ds_read_b128 v[198:201], v255
	ds_read_b128 v[152:155], v255 offset:2048
	ds_read_b128 v[120:123], v254 offset:4096
	ds_read_b128 v[112:115], v254 offset:6144
	ds_read_b128 v[124:127], v255 offset:4096
	ds_read_b128 v[116:119], v255 offset:6144
	v_max_f32_e32 v1, v160, v161
	v_max3_f32 v1, v1, v162, v163
	v_max3_f32 v1, v1, v164, v165
	v_max3_f32 v1, v1, v166, v167
	v_max3_f32 v1, v1, v168, v169
	v_max3_f32 v1, v1, v170, v171
	v_max3_f32 v1, v1, v172, v173
	v_max3_f32 v1, v1, v174, v175
	v_max3_f32 v1, v1, v128, v129
	v_max3_f32 v1, v1, v130, v131
	v_max3_f32 v1, v1, v132, v133
	v_max3_f32 v1, v1, v134, v135
	v_max3_f32 v1, v1, v136, v137
	v_max3_f32 v1, v1, v138, v139
	v_max3_f32 v1, v1, v140, v141
	v_max3_f32 v1, v1, v142, v143
	v_cmp_lt_f32_e32 vcc, s80, v1
	s_cbranch_vccnz .LBB0_383

; #define SBAR() __builtin_amdgcn_sched_barrier(0)
; #define MFMA8Q(A, B, C) __builtin_amdgcn_mfma_scale_f32_32x32x64_f8f6f4(A, B, C, 0, 0, 0, SCL1, 0, 0x7C7C7C7C)
; __device__ __forceinline__ v8i ld32(const char* p0, const char* p1) { const u32x4 a = *(const u32x4*)p0, b = *(const u32x4*)p1; return (v8i){(int)a.x, (int)a.y, (int)a.z, (int)a.w, (int)b.x, (int)b.y, (int)b.z, (int)b.w}; }
; #define DMA(slot, t) do { \
;     __builtin_amdgcn_global_load_lds((const unsigned*)(Kg + (long)(t) * (64 * 256)), (LAS unsigned*)(L3 + K_OFF + (slot) * SHM_T + wid * 1024), 16, 0, 0); \
;     __builtin_amdgcn_global_load_lds((const unsigned*)(Vg + (long)(t) * 8192), (LAS unsigned*)(L3 + (slot) * SHM_T + wid * 1024), 16, 0, 0); } while (0)
; __device__ __forceinline__ void finishSM(f32x16& p0, f32x16& p1, v8i& pf) {
;   for (int r = 0; r < 16; ++r) p1[r] = __builtin_amdgcn_exp2f(p1[r]);
; #pragma unroll
;   for (int j = 0; j < 4; ++j) {
;     int a = __builtin_amdgcn_cvt_pk_fp8_f32(p0[4 * j], p0[4 * j + 1], 0, false); a = __builtin_amdgcn_cvt_pk_fp8_f32(p0[4 * j + 2], p0[4 * j + 3], a, true);
;     int b = __builtin_amdgcn_cvt_pk_fp8_f32(p1[4 * j], p1[4 * j + 1], 0, false); b = __builtin_amdgcn_cvt_pk_fp8_f32(p1[4 * j + 2], p1[4 * j + 3], b, true);
;     auto rr = __builtin_amdgcn_permlane32_swap((unsigned)a, (unsigned)b, false, false);
;     pf[2 * j] = (int)rr[0]; pf[2 * j + 1] = (int)rr[1]; }
; }
; __device__ __forceinline__ void qkt(f32x16& p0, f32x16& p1, const f32x16& nm, const char* Ks, const v8i* qr, int ko, int c00, int c01, int c10, int c11) {
;   { const v8i a0 = ld32(Ks + ko + c00, Ks + ko + c01), a1 = ld32(Ks + 4096 + ko + c00, Ks + 4096 + ko + c01);
;     p0 = MFMA8Q(a0, qr[0], nm); p1 = MFMA8Q(a1, qr[0], nm); }
;   { const v8i a0 = ld32(Ks + ko + c10, Ks + ko + c11), a1 = ld32(Ks + 4096 + ko + c10, Ks + 4096 + ko + c11);
;     p0 = MFMA8Q(a0, qr[1], p0); p1 = MFMA8Q(a1, qr[1], p1); }
; }
; __device__ __forceinline__ void body(const unsigned char* Q8b, const unsigned char* K8h, const unsigned char* VT8h, const bf16_t* Gb, bf16_t* Ob, int seq, char* lds, const int wid, ...
;     ...
;     SBAR(); QKT(pA0, pA1, (s0 + 2) & 3);
;     finishSM(pB0, pB1, pf); PIPE1(); SBAR();
;     { const int t4 = (i + 4 < NT) ? i + 4 : NT - 1; DMA(s0, t4); }
;     SBAR();
;     HALF2(pA0, pA1, alA, (s0 + 1) & 3);
.Lstg_a1:
	ds_read_b128 v[2:5], v242 offset:49152
	ds_read_b128 v[6:9], v243 offset:49152
	ds_read_b128 v[112:115], v242 offset:53248
	ds_read_b128 v[116:119], v243 offset:53248
	ds_read_b128 v[194:197], v244 offset:49152
	ds_read_b128 v[198:201], v245 offset:49152
	ds_read_b128 v[246:249], v244 offset:53248
	ds_read_b128 v[250:253], v245 offset:53248
	v_exp_f32_e32 v1, v128
	v_exp_f32_e32 v10, v129
	v_exp_f32_e32 v11, v130
	v_exp_f32_e32 v12, v131
	s_waitcnt lgkmcnt(6)
	s_setprio 1
	v_mfma_scale_f32_32x32x64_f8f6f4 v[160:175], v[2:9], v[176:183], v[96:111], v240, v239 op_sel_hi:[0,0,0]
	v_exp_f32_e32 v6, v132
	v_exp_f32_e32 v7, v133
	v_exp_f32_e32 v8, v134
	v_exp_f32_e32 v9, v135
	v_cvt_pk_fp8_f32 v5, v6, v7
	v_cvt_pk_fp8_f32 v2, v144, v145
	v_cvt_pk_fp8_f32 v5, v8, v9 op_sel:[0,0,1]
	s_waitcnt lgkmcnt(4)
	v_mfma_scale_f32_32x32x64_f8f6f4 v[112:127], v[112:119], v[176:183], v[96:111], v240, v239 op_sel_hi:[0,0,0]
	v_exp_f32_e32 v13, v136
	v_exp_f32_e32 v14, v137
	v_exp_f32_e32 v15, v138
	v_exp_f32_e32 v128, v139
	v_cvt_pk_fp8_f32 v3, v1, v10
	v_cvt_pk_fp8_f32 v4, v148, v149
	v_cvt_pk_fp8_f32 v6, v152, v153
	v_cvt_pk_fp8_f32 v7, v13, v14
	v_cvt_pk_fp8_f32 v8, v156, v157
	v_cvt_pk_fp8_f32 v2, v146, v147 op_sel:[0,0,1]
	v_cvt_pk_fp8_f32 v3, v11, v12 op_sel:[0,0,1]
	v_cvt_pk_fp8_f32 v4, v150, v151 op_sel:[0,0,1]
	v_cvt_pk_fp8_f32 v6, v154, v155 op_sel:[0,0,1]
	v_cvt_pk_fp8_f32 v7, v15, v128 op_sel:[0,0,1]
	v_cvt_pk_fp8_f32 v8, v158, v159 op_sel:[0,0,1]
	s_waitcnt lgkmcnt(2)
	v_mfma_scale_f32_32x32x64_f8f6f4 v[160:175], v[194:201], v[184:191], v[160:175], v240, v239 op_sel_hi:[0,0,0]
	v_exp_f32_e32 v129, v140
	v_exp_f32_e32 v130, v141
	v_exp_f32_e32 v131, v142
	v_exp_f32_e32 v132, v143
	v_cvt_pk_fp8_f32 v9, v129, v130
	s_nop 0
	v_cvt_pk_fp8_f32 v9, v131, v132 op_sel:[0,0,1]
	s_waitcnt lgkmcnt(0)
	v_mfma_scale_f32_32x32x64_f8f6f4 v[112:127], v[246:253], v[184:191], v[112:127], v240, v239 op_sel_hi:[0,0,0]
	s_setprio 0
	s_min_u32 s36, s45, 0x7b
	s_add_i32 s56, s36, 4
	s_lshl_b32 s36, s56, 14
	s_add_i32 s57, s68, 0x0
	s_add_u32 s88, s94, s36
	s_addc_u32 s89, s95, 0
	s_add_i32 m0, s57, 0x8000
	s_lshl_b32 s36, s56, 13
	s_add_u32 s90, s96, s36
	s_addc_u32 s91, s97, 0
	global_load_lds_dwordx4 v192, s[88:89]
	s_mov_b32 m0, s57
	s_nop 0
	global_load_lds_dwordx4 v193, s[90:91]
	ds_read_b128 v[194:197], v254 offset:8192
	ds_read_b128 v[148:151], v254 offset:10240
	ds_read_b128 v[198:201], v255 offset:8192
	ds_read_b128 v[152:155], v255 offset:10240
	ds_read_b128 v[136:139], v254 offset:12288
	ds_read_b128 v[128:131], v254 offset:14336
	ds_read_b128 v[140:143], v255 offset:12288
	ds_read_b128 v[132:135], v255 offset:14336
	v_max_f32_e32 v1, v160, v161
	v_max3_f32 v1, v1, v162, v163
	v_max3_f32 v1, v1, v164, v165
	v_max3_f32 v1, v1, v166, v167
	v_max3_f32 v1, v1, v168, v169
	v_max3_f32 v1, v1, v170, v171
	v_max3_f32 v1, v1, v172, v173
	v_max3_f32 v1, v1, v174, v175
	v_max3_f32 v1, v1, v112, v113
	v_max3_f32 v1, v1, v114, v115
	v_max3_f32 v1, v1, v116, v117
	v_max3_f32 v1, v1, v118, v119
	v_max3_f32 v1, v1, v120, v121
	v_max3_f32 v1, v1, v122, v123
	v_max3_f32 v1, v1, v124, v125
	v_max3_f32 v1, v1, v126, v127
	v_cmp_lt_f32_e32 vcc, s80, v1
	s_cbranch_vccnz .LBB0_384

; #define SBAR() __builtin_amdgcn_sched_barrier(0)
; #define MFMA8Q(A, B, C) __builtin_amdgcn_mfma_scale_f32_32x32x64_f8f6f4(A, B, C, 0, 0, 0, SCL1, 0, 0x7C7C7C7C)
; __device__ __forceinline__ v8i ld32(const char* p0, const char* p1) { const u32x4 a = *(const u32x4*)p0, b = *(const u32x4*)p1; return (v8i){(int)a.x, (int)a.y, (int)a.z, (int)a.w, (int)b.x, (int)b.y, (int)b.z, (int)b.w}; }
; #define DMA(slot, t) do { \
;     __builtin_amdgcn_global_load_lds((const unsigned*)(Kg + (long)(t) * (64 * 256)), (LAS unsigned*)(L3 + K_OFF + (slot) * SHM_T + wid * 1024), 16, 0, 0); \
;     __builtin_amdgcn_global_load_lds((const unsigned*)(Vg + (long)(t) * 8192), (LAS unsigned*)(L3 + (slot) * SHM_T + wid * 1024), 16, 0, 0); } while (0)
; #define QKT(P0, P1, b) qkt(P0, P1, nm, K_lds + (b) * SHM_T, qr, ko, c00, c01, c10, c11)
; __device__ __forceinline__ void finishSM(f32x16& p0, f32x16& p1, v8i& pf) {
;   for (int r = 0; r < 16; ++r) p1[r] = __builtin_amdgcn_exp2f(p1[r]);
; #pragma unroll
;   for (int j = 0; j < 4; ++j) {
;     int a = __builtin_amdgcn_cvt_pk_fp8_f32(p0[4 * j], p0[4 * j + 1], 0, false); a = __builtin_amdgcn_cvt_pk_fp8_f32(p0[4 * j + 2], p0[4 * j + 3], a, true);
;     int b = __builtin_amdgcn_cvt_pk_fp8_f32(p1[4 * j], p1[4 * j + 1], 0, false); b = __builtin_amdgcn_cvt_pk_fp8_f32(p1[4 * j + 2], p1[4 * j + 3], b, true);
;     auto rr = __builtin_amdgcn_permlane32_swap((unsigned)a, (unsigned)b, false, false);
;     pf[2 * j] = (int)rr[0]; pf[2 * j + 1] = (int)rr[1]; }
; }
; __device__ __forceinline__ void qkt(f32x16& p0, f32x16& p1, const f32x16& nm, const char* Ks, const v8i* qr, int ko, int c00, int c01, int c10, int c11) {
;   { const v8i a0 = ld32(Ks + ko + c00, Ks + ko + c01), a1 = ld32(Ks + 4096 + ko + c00, Ks + 4096 + ko + c01);
;     p0 = MFMA8Q(a0, qr[0], nm); p1 = MFMA8Q(a1, qr[0], nm); }
;   { const v8i a0 = ld32(Ks + ko + c10, Ks + ko + c11), a1 = ld32(Ks + 4096 + ko + c10, Ks + 4096 + ko + c11);
;     p0 = MFMA8Q(a0, qr[1], p0); p1 = MFMA8Q(a1, qr[1], p1); }
; }
; __device__ __forceinline__ void body(const unsigned char* Q8b, const unsigned char* K8h, const unsigned char* VT8h, const bf16_t* Gb, bf16_t* Ob, int seq, char* lds, const int wid, ...
;     ...
;     SBAR(); QKT(pB0, pB1, (s0 + 1) & 3);
;     finishSM(pA0, pA1, pf); PIPE1(); SBAR();
;     DMA((s0 + 3) & 3, i + 3);
;     SBAR();
;     HALF2(pB0, pB1, alB, s0);
.Lc2_374:
	ds_read_b128 v[2:5], v242 offset:57344
	ds_read_b128 v[6:9], v243 offset:57344
	ds_read_b128 v[128:131], v242 offset:61440
	ds_read_b128 v[132:135], v243 offset:61440
	ds_read_b128 v[194:197], v244 offset:57344
	ds_read_b128 v[198:201], v245 offset:57344
	ds_read_b128 v[246:249], v244 offset:61440
	ds_read_b128 v[250:253], v245 offset:61440
	v_exp_f32_e32 v1, v112
	v_exp_f32_e32 v10, v113
	v_exp_f32_e32 v11, v114
	v_exp_f32_e32 v12, v115
	s_waitcnt lgkmcnt(6)
	s_setprio 1
	v_mfma_scale_f32_32x32x64_f8f6f4 v[160:175], v[2:9], v[176:183], v[96:111], v240, v239 op_sel_hi:[0,0,0]
	v_exp_f32_e32 v6, v116
	v_exp_f32_e32 v7, v117
	v_exp_f32_e32 v8, v118
	v_exp_f32_e32 v9, v119
	v_cvt_pk_fp8_f32 v5, v6, v7
	v_cvt_pk_fp8_f32 v3, v1, v10
	v_cvt_pk_fp8_f32 v5, v8, v9 op_sel:[0,0,1]
	s_waitcnt lgkmcnt(4)
	v_mfma_scale_f32_32x32x64_f8f6f4 v[128:143], v[128:135], v[176:183], v[96:111], v240, v239 op_sel_hi:[0,0,0]
	v_exp_f32_e32 v13, v120
	v_exp_f32_e32 v14, v121
	v_exp_f32_e32 v15, v122
	v_exp_f32_e32 v112, v123
	v_cvt_pk_fp8_f32 v2, v144, v145
	v_cvt_pk_fp8_f32 v4, v148, v149
	v_cvt_pk_fp8_f32 v6, v152, v153
	v_cvt_pk_fp8_f32 v7, v13, v14
	v_cvt_pk_fp8_f32 v8, v156, v157
	v_cvt_pk_fp8_f32 v2, v146, v147 op_sel:[0,0,1]
	v_cvt_pk_fp8_f32 v3, v11, v12 op_sel:[0,0,1]
	v_cvt_pk_fp8_f32 v4, v150, v151 op_sel:[0,0,1]
	v_cvt_pk_fp8_f32 v6, v154, v155 op_sel:[0,0,1]
	v_cvt_pk_fp8_f32 v7, v15, v112 op_sel:[0,0,1]
	v_cvt_pk_fp8_f32 v8, v158, v159 op_sel:[0,0,1]
	s_waitcnt lgkmcnt(2)
	v_mfma_scale_f32_32x32x64_f8f6f4 v[160:175], v[194:201], v[184:191], v[160:175], v240, v239 op_sel_hi:[0,0,0]
	v_exp_f32_e32 v113, v124
	v_exp_f32_e32 v114, v125
	v_exp_f32_e32 v1, v126
	v_exp_f32_e32 v10, v127
	v_cvt_pk_fp8_f32 v9, v113, v114
	s_nop 0
	v_cvt_pk_fp8_f32 v9, v1, v10 op_sel:[0,0,1]
	s_waitcnt lgkmcnt(0)
	v_mfma_scale_f32_32x32x64_f8f6f4 v[128:143], v[246:253], v[184:191], v[128:143], v240, v239 op_sel_hi:[0,0,0]
	s_setprio 0
	s_add_i32 m0, s68, 0xa000
	s_nop 0
	global_load_lds_dwordx4 v192, s[98:99]
	s_add_i32 m0, s68, 0x2000
	s_nop 0
	global_load_lds_dwordx4 v193, s[100:101]
	ds_read_b128 v[194:197], v254 offset:16384
	ds_read_b128 v[148:151], v254 offset:18432
	ds_read_b128 v[198:201], v255 offset:16384
	ds_read_b128 v[152:155], v255 offset:18432
	ds_read_b128 v[120:123], v254 offset:20480
	ds_read_b128 v[112:115], v254 offset:22528
	ds_read_b128 v[124:127], v255 offset:20480
	ds_read_b128 v[116:119], v255 offset:22528
	v_max_f32_e32 v1, v160, v161
	v_max3_f32 v1, v1, v162, v163
	v_max3_f32 v1, v1, v164, v165
	v_max3_f32 v1, v1, v166, v167
	v_max3_f32 v1, v1, v168, v169
	v_max3_f32 v1, v1, v170, v171
	v_max3_f32 v1, v1, v172, v173
	v_max3_f32 v1, v1, v174, v175
	v_max3_f32 v1, v1, v128, v129
	v_max3_f32 v1, v1, v130, v131
	v_max3_f32 v1, v1, v132, v133
	v_max3_f32 v1, v1, v134, v135
	v_max3_f32 v1, v1, v136, v137
	v_max3_f32 v1, v1, v138, v139
	v_max3_f32 v1, v1, v140, v141
	v_max3_f32 v1, v1, v142, v143
	v_cmp_lt_f32_e32 vcc, s80, v1
	s_cbranch_vccnz .Lc2_383

; #define SBAR() __builtin_amdgcn_sched_barrier(0)
; #define MFMA8Q(A, B, C) __builtin_amdgcn_mfma_scale_f32_32x32x64_f8f6f4(A, B, C, 0, 0, 0, SCL1, 0, 0x7C7C7C7C)
; __device__ __forceinline__ v8i ld32(const char* p0, const char* p1) { const u32x4 a = *(const u32x4*)p0, b = *(const u32x4*)p1; return (v8i){(int)a.x, (int)a.y, (int)a.z, (int)a.w, (int)b.x, (int)b.y, (int)b.z, (int)b.w}; }
; #define DMA(slot, t) do { \
;     __builtin_amdgcn_global_load_lds((const unsigned*)(Kg + (long)(t) * (64 * 256)), (LAS unsigned*)(L3 + K_OFF + (slot) * SHM_T + wid * 1024), 16, 0, 0); \
;     __builtin_amdgcn_global_load_lds((const unsigned*)(Vg + (long)(t) * 8192), (LAS unsigned*)(L3 + (slot) * SHM_T + wid * 1024), 16, 0, 0); } while (0)
; __device__ __forceinline__ void finishSM(f32x16& p0, f32x16& p1, v8i& pf) {
;   for (int r = 0; r < 16; ++r) p1[r] = __builtin_amdgcn_exp2f(p1[r]);
; #pragma unroll
;   for (int j = 0; j < 4; ++j) {
;     int a = __builtin_amdgcn_cvt_pk_fp8_f32(p0[4 * j], p0[4 * j + 1], 0, false); a = __builtin_amdgcn_cvt_pk_fp8_f32(p0[4 * j + 2], p0[4 * j + 3], a, true);
;     int b = __builtin_amdgcn_cvt_pk_fp8_f32(p1[4 * j], p1[4 * j + 1], 0, false); b = __builtin_amdgcn_cvt_pk_fp8_f32(p1[4 * j + 2], p1[4 * j + 3], b, true);
;     auto rr = __builtin_amdgcn_permlane32_swap((unsigned)a, (unsigned)b, false, false);
;     pf[2 * j] = (int)rr[0]; pf[2 * j + 1] = (int)rr[1]; }
; }
; __device__ __forceinline__ void qkt(f32x16& p0, f32x16& p1, const f32x16& nm, const char* Ks, const v8i* qr, int ko, int c00, int c01, int c10, int c11) {
;   { const v8i a0 = ld32(Ks + ko + c00, Ks + ko + c01), a1 = ld32(Ks + 4096 + ko + c00, Ks + 4096 + ko + c01);
;     p0 = MFMA8Q(a0, qr[0], nm); p1 = MFMA8Q(a1, qr[0], nm); }
;   { const v8i a0 = ld32(Ks + ko + c10, Ks + ko + c11), a1 = ld32(Ks + 4096 + ko + c10, Ks + 4096 + ko + c11);
;     p0 = MFMA8Q(a0, qr[1], p0); p1 = MFMA8Q(a1, qr[1], p1); }
; }
; __device__ __forceinline__ void body(const unsigned char* Q8b, const unsigned char* K8h, const unsigned char* VT8h, const bf16_t* Gb, bf16_t* Ob, int seq, char* lds, const int wid, ...
;     ...
;     SBAR(); QKT(pA0, pA1, (s0 + 2) & 3);
;     finishSM(pB0, pB1, pf); PIPE1(); SBAR();
;     { const int t4 = (i + 4 < NT) ? i + 4 : NT - 1; DMA(s0, t4); }
;     SBAR();
;     HALF2(pA0, pA1, alA, (s0 + 1) & 3);
.Lc2stg_a1:
	ds_read_b128 v[2:5], v242 offset:32768
	ds_read_b128 v[6:9], v243 offset:32768
	ds_read_b128 v[112:115], v242 offset:36864
	ds_read_b128 v[116:119], v243 offset:36864
	ds_read_b128 v[194:197], v244 offset:32768
	ds_read_b128 v[198:201], v245 offset:32768
	ds_read_b128 v[246:249], v244 offset:36864
	ds_read_b128 v[250:253], v245 offset:36864
	v_exp_f32_e32 v1, v128
	v_exp_f32_e32 v10, v129
	v_exp_f32_e32 v11, v130
	v_exp_f32_e32 v12, v131
	s_waitcnt lgkmcnt(6)
	s_setprio 1
	v_mfma_scale_f32_32x32x64_f8f6f4 v[160:175], v[2:9], v[176:183], v[96:111], v240, v239 op_sel_hi:[0,0,0]
	v_exp_f32_e32 v6, v132
	v_exp_f32_e32 v7, v133
	v_exp_f32_e32 v8, v134
	v_exp_f32_e32 v9, v135
	v_cvt_pk_fp8_f32 v5, v6, v7
	v_cvt_pk_fp8_f32 v2, v144, v145
	v_cvt_pk_fp8_f32 v5, v8, v9 op_sel:[0,0,1]
	s_waitcnt lgkmcnt(4)
	v_mfma_scale_f32_32x32x64_f8f6f4 v[112:127], v[112:119], v[176:183], v[96:111], v240, v239 op_sel_hi:[0,0,0]
	v_exp_f32_e32 v13, v136
	v_exp_f32_e32 v14, v137
	v_exp_f32_e32 v15, v138
	v_exp_f32_e32 v128, v139
	v_cvt_pk_fp8_f32 v3, v1, v10
	v_cvt_pk_fp8_f32 v4, v148, v149
	v_cvt_pk_fp8_f32 v6, v152, v153
	v_cvt_pk_fp8_f32 v7, v13, v14
	v_cvt_pk_fp8_f32 v8, v156, v157
	v_cvt_pk_fp8_f32 v2, v146, v147 op_sel:[0,0,1]
	v_cvt_pk_fp8_f32 v3, v11, v12 op_sel:[0,0,1]
	v_cvt_pk_fp8_f32 v4, v150, v151 op_sel:[0,0,1]
	v_cvt_pk_fp8_f32 v6, v154, v155 op_sel:[0,0,1]
	v_cvt_pk_fp8_f32 v7, v15, v128 op_sel:[0,0,1]
	v_cvt_pk_fp8_f32 v8, v158, v159 op_sel:[0,0,1]
	s_waitcnt lgkmcnt(2)
	v_mfma_scale_f32_32x32x64_f8f6f4 v[160:175], v[194:201], v[184:191], v[160:175], v240, v239 op_sel_hi:[0,0,0]
	v_exp_f32_e32 v129, v140
	v_exp_f32_e32 v130, v141
	v_exp_f32_e32 v131, v142
	v_exp_f32_e32 v132, v143
	v_cvt_pk_fp8_f32 v9, v129, v130
	s_nop 0
	v_cvt_pk_fp8_f32 v9, v131, v132 op_sel:[0,0,1]
	s_waitcnt lgkmcnt(0)
	v_mfma_scale_f32_32x32x64_f8f6f4 v[112:127], v[246:253], v[184:191], v[112:127], v240, v239 op_sel_hi:[0,0,0]
	s_setprio 0
	s_min_u32 s36, s45, 0x7b
	s_add_i32 s56, s36, 4
	s_lshl_b32 s36, s56, 14
	s_add_i32 s57, s68, 0x4000
	s_add_u32 s88, s94, s36
	s_addc_u32 s89, s95, 0
	s_add_i32 m0, s57, 0x8000
	s_lshl_b32 s36, s56, 13
	s_add_u32 s90, s96, s36
	s_addc_u32 s91, s97, 0
	global_load_lds_dwordx4 v192, s[88:89]
	s_mov_b32 m0, s57
	s_nop 0
	global_load_lds_dwordx4 v193, s[90:91]
	ds_read_b128 v[194:197], v254 offset:24576
	ds_read_b128 v[148:151], v254 offset:26624
	ds_read_b128 v[198:201], v255 offset:24576
	ds_read_b128 v[152:155], v255 offset:26624
	ds_read_b128 v[136:139], v254 offset:28672
	ds_read_b128 v[128:131], v254 offset:30720
	ds_read_b128 v[140:143], v255 offset:28672
	ds_read_b128 v[132:135], v255 offset:30720
	v_max_f32_e32 v1, v160, v161
	v_max3_f32 v1, v1, v162, v163
	v_max3_f32 v1, v1, v164, v165
	v_max3_f32 v1, v1, v166, v167
	v_max3_f32 v1, v1, v168, v169
	v_max3_f32 v1, v1, v170, v171
	v_max3_f32 v1, v1, v172, v173
	v_max3_f32 v1, v1, v174, v175
	v_max3_f32 v1, v1, v112, v113
	v_max3_f32 v1, v1, v114, v115
	v_max3_f32 v1, v1, v116, v117
	v_max3_f32 v1, v1, v118, v119
	v_max3_f32 v1, v1, v120, v121
	v_max3_f32 v1, v1, v122, v123
	v_max3_f32 v1, v1, v124, v125
	v_max3_f32 v1, v1, v126, v127
	v_cmp_lt_f32_e32 vcc, s80, v1
	s_cbranch_vccnz .Lc2_384

; #define SBAR() __builtin_amdgcn_sched_barrier(0)
; #define MFMA8Q(A, B, C) __builtin_amdgcn_mfma_scale_f32_32x32x64_f8f6f4(A, B, C, 0, 0, 0, SCL1, 0, 0x7C7C7C7C)
; __device__ __forceinline__ v8i ld32(const char* p0, const char* p1) { const u32x4 a = *(const u32x4*)p0, b = *(const u32x4*)p1; return (v8i){(int)a.x, (int)a.y, (int)a.z, (int)a.w, (int)b.x, (int)b.y, (int)b.z, (int)b.w}; }
; #define QKT(P0, P1, b) qkt(P0, P1, nm, K_lds + (b) * SHM_T, qr, ko, c00, c01, c10, c11)
; #define HALF2(Y0, Y1, alY, b) do { PVL(b); const float pm_ = max32(Y0, Y1); adjustSM(Y0, Y1, nm, alY, pm_); SBAR(); \
;     PVM(); exp16(Y0); asm volatile("" : "+v"(Y0)); \
;     SGB(0x008, 1); SGB(0x400, 3); SGB(0x008, 1); SGB(0x400, 3); SGB(0x008, 1); SGB(0x400, 3); SGB(0x008, 1); SGB(0x400, 3); SGB(0x008, 1); SGB(0x400, 4); SBAR(); } while (0)
; __device__ __forceinline__ void finishSM(f32x16& p0, f32x16& p1, v8i& pf) {
;   for (int r = 0; r < 16; ++r) p1[r] = __builtin_amdgcn_exp2f(p1[r]);
; #pragma unroll
;   for (int j = 0; j < 4; ++j) {
;     int a = __builtin_amdgcn_cvt_pk_fp8_f32(p0[4 * j], p0[4 * j + 1], 0, false); a = __builtin_amdgcn_cvt_pk_fp8_f32(p0[4 * j + 2], p0[4 * j + 3], a, true);
;     int b = __builtin_amdgcn_cvt_pk_fp8_f32(p1[4 * j], p1[4 * j + 1], 0, false); b = __builtin_amdgcn_cvt_pk_fp8_f32(p1[4 * j + 2], p1[4 * j + 3], b, true);
;     auto rr = __builtin_amdgcn_permlane32_swap((unsigned)a, (unsigned)b, false, false);
;     pf[2 * j] = (int)rr[0]; pf[2 * j + 1] = (int)rr[1]; }
; }
; __device__ __forceinline__ void qkt(f32x16& p0, f32x16& p1, const f32x16& nm, const char* Ks, const v8i* qr, int ko, int c00, int c01, int c10, int c11) {
;   { const v8i a0 = ld32(Ks + ko + c00, Ks + ko + c01), a1 = ld32(Ks + 4096 + ko + c00, Ks + 4096 + ko + c01);
;     p0 = MFMA8Q(a0, qr[0], nm); p1 = MFMA8Q(a1, qr[0], nm); }
;   { const v8i a0 = ld32(Ks + ko + c10, Ks + ko + c11), a1 = ld32(Ks + 4096 + ko + c10, Ks + 4096 + ko + c11);
;     p0 = MFMA8Q(a0, qr[1], p0); p1 = MFMA8Q(a1, qr[1], p1); }
; }
; __device__ __forceinline__ void body(const unsigned char* Q8b, const unsigned char* K8h, const unsigned char* VT8h, const bf16_t* Gb, bf16_t* Ob, int seq, char* lds, const int wid, ...
;     ...
;   SBAR(); QKT(pB0, pB1, (s0 + 1) & 3);
;   finishSM(pA0, pA1, pf); SBAR();
;   HALF2(pB0, pB1, alB, s0);
.LBB0_385:
	ds_read_b128 v[6:9], v243 offset:57344
	ds_read_b128 v[2:5], v242 offset:57344
	ds_read_b128 v[160:163], v242 offset:61440
	ds_read_b128 v[164:167], v243 offset:61440
	ds_read_b128 v[168:171], v244 offset:57344
	ds_read_b128 v[194:197], v244 offset:61440
	ds_read_b128 v[172:175], v245 offset:57344
	ds_read_b128 v[198:201], v245 offset:61440
	s_waitcnt lgkmcnt(0)
	v_mfma_scale_f32_32x32x64_f8f6f4 v[128:143], v[2:9], v[176:183], v[96:111], v240, v239 op_sel_hi:[0,0,0]
	v_exp_f32_e32 v1, v112
	v_exp_f32_e32 v10, v113
	v_mov_b32_e32 v3, v0
	v_exp_f32_e32 v6, v114
	v_exp_f32_e32 v7, v115
	v_exp_f32_e32 v8, v116
	v_exp_f32_e32 v9, v117
	v_cvt_pk_fp8_f32 v3, v1, v10
	v_exp_f32_e32 v13, v120
	v_exp_f32_e32 v14, v121
	v_exp_f32_e32 v113, v124
	v_exp_f32_e32 v114, v125
	v_mov_b32_e32 v5, v0
	v_mov_b32_e32 v2, v0
	v_mov_b32_e32 v4, v0
	v_mfma_scale_f32_32x32x64_f8f6f4 v[96:111], v[160:167], v[176:183], v[96:111], v240, v239 op_sel_hi:[0,0,0]
	v_cvt_pk_fp8_f32 v5, v8, v9
	v_cvt_pk_fp8_f32 v3, v6, v7 op_sel:[0,0,1]
	v_mov_b32_e32 v6, v0
	v_mov_b32_e32 v7, v0
	v_mov_b32_e32 v8, v0
	v_mov_b32_e32 v9, v0
	v_exp_f32_e32 v11, v118
	v_exp_f32_e32 v12, v119
	v_exp_f32_e32 v15, v122
	v_exp_f32_e32 v112, v123
	v_exp_f32_e32 v115, v126
	v_exp_f32_e32 v116, v127
	v_cvt_pk_fp8_f32 v2, v144, v145
	v_cvt_pk_fp8_f32 v4, v148, v149
	v_cvt_pk_fp8_f32 v6, v152, v153
	v_mfma_scale_f32_32x32x64_f8f6f4 v[128:143], v[168:175], v[184:191], v[128:143], v240, v239 op_sel_hi:[0,0,0]
	v_cvt_pk_fp8_f32 v7, v13, v14
	v_cvt_pk_fp8_f32 v8, v156, v157
	v_cvt_pk_fp8_f32 v9, v113, v114
	v_cvt_pk_fp8_f32 v2, v146, v147 op_sel:[0,0,1]
	v_cvt_pk_fp8_f32 v4, v150, v151 op_sel:[0,0,1]
	v_cvt_pk_fp8_f32 v5, v11, v12 op_sel:[0,0,1]
	v_cvt_pk_fp8_f32 v6, v154, v155 op_sel:[0,0,1]
	v_cvt_pk_fp8_f32 v7, v15, v112 op_sel:[0,0,1]
	v_cvt_pk_fp8_f32 v8, v158, v159 op_sel:[0,0,1]
	v_cvt_pk_fp8_f32 v9, v115, v116 op_sel:[0,0,1]
	s_nop 0
	v_mfma_scale_f32_32x32x64_f8f6f4 v[96:111], v[194:201], v[184:191], v[96:111], v240, v239 op_sel_hi:[0,0,0]
	s_nop 4
	v_max_f32_e32 v11, v129, v129
	v_max_f32_e32 v12, v128, v128
	v_max_f32_e32 v11, v12, v11
	v_max3_f32 v11, v11, v130, v131
	v_max3_f32 v11, v11, v132, v133
	v_max3_f32 v11, v11, v134, v135
	v_max3_f32 v11, v11, v136, v137
	v_max3_f32 v11, v11, v138, v139
	v_max3_f32 v11, v11, v140, v141
	v_max3_f32 v11, v11, v142, v143
	s_nop 3
	v_max3_f32 v11, v11, v96, v97
	v_mov_b32_e32 v1, v254
	v_max3_f32 v11, v11, v98, v99
	v_mov_b32_e32 v10, v255
	ds_read_b128 v[160:163], v1 offset:16384
	ds_read_b128 v[152:155], v1 offset:18432
	ds_read_b128 v[164:167], v10 offset:16384
	ds_read_b128 v[156:159], v10 offset:18432
	ds_read_b128 v[118:121], v1 offset:20480
	ds_read_b128 v[144:147], v1 offset:22528
	ds_read_b128 v[122:125], v10 offset:20480
	ds_read_b128 v[148:151], v10 offset:22528
	v_max3_f32 v11, v11, v100, v101
	v_max3_f32 v11, v11, v102, v103
	v_max3_f32 v11, v11, v104, v105
	v_max3_f32 v11, v11, v106, v107
	v_max3_f32 v11, v11, v108, v109
	v_max3_f32 v11, v11, v110, v111
	v_mov_b32_e32 v12, v11
	s_nop 1
	v_permlane32_swap_b32_e32 v11, v12
	v_max_f32_e32 v12, v12, v12
	v_max_f32_e32 v11, v11, v11
	v_max_f32_e32 v12, v11, v12
	v_cmp_lt_f32_e32 vcc, s80, v12
	v_mov_b32_e32 v11, 1.0
	s_cbranch_vccnz .LBB0_392

; #define LAS __attribute__((address_space(3)))
; #define SBAR() __builtin_amdgcn_sched_barrier(0)
; #define WAITV(n) asm volatile("s_waitcnt vmcnt(" #n ")" ::: "memory")
; #define PVL(b) pv_load(vf, V_lds + (b) * SHM_T, vo, e0, e1)
; #define PVM() pv_mma(o, ls, vf, pf)
; #define lane lane_id()
; __device__ __forceinline__ void body(const unsigned char* Q8b, const unsigned char* K8h, const unsigned char* VT8h, const bf16_t* Gb, bf16_t* Ob, int seq, char* lds, const int wid, ...
;     ...
;   PVL((s0 + 1) & 3); finishSM(pB0, pB1, pf); SBAR();
;   PVM();
;   WAITV(0);
;   if (nxt) {
;     load_q(qr, Q8n, wid, r32, hi);
;     const char* KgN = (const char*)K8n + krow * 256 + kc * 16; const char* VgN = (const char*)VT8n + wid * 1024 + lane * 16;
; #pragma unroll
;     for (int tn = 0; tn < 2; ++tn) {
;       __builtin_amdgcn_global_load_lds((const unsigned*)(KgN + (long)tn * (64 * 256)), (LAS unsigned*)(L3 + K_OFF + tn * SHM_T + wid * 1024), 16, 0, 0);
;       __builtin_amdgcn_global_load_lds((const unsigned*)(VgN + (long)tn * 8192), (LAS unsigned*)(L3 + tn * SHM_T + wid * 1024), 16, 0, 0); }
;   }
.LBB0_390:
	v_exp_f32_e32 v13, v100
	v_exp_f32_e32 v14, v101
	v_exp_f32_e32 v12, v99
	v_mov_b32_e32 v99, v0
	v_exp_f32_e32 v15, v102
	v_exp_f32_e32 v100, v103
	v_exp_f32_e32 v102, v104
	v_exp_f32_e32 v103, v105
	v_cvt_pk_fp8_f32 v99, v13, v14
	ds_read_b128 v[144:147], v1 offset:24576
	ds_read_b128 v[136:139], v1 offset:26624
	ds_read_b128 v[148:151], v10 offset:24576
	ds_read_b128 v[140:143], v10 offset:26624
	ds_read_b128 v[128:131], v1 offset:28672
	ds_read_b128 v[2:5], v1 offset:30720
	ds_read_b128 v[132:135], v10 offset:28672
	ds_read_b128 v[6:9], v10 offset:30720
	v_exp_f32_e32 v1, v96
	v_exp_f32_e32 v10, v97
	v_exp_f32_e32 v104, v106
	v_exp_f32_e32 v105, v107
	v_exp_f32_e32 v106, v108
	v_exp_f32_e32 v107, v109
	v_mov_b32_e32 v101, v0
	v_exp_f32_e32 v11, v98
	v_mov_b32_e32 v96, v0
	v_mov_b32_e32 v97, v0
	v_mov_b32_e32 v98, v0
	v_cvt_pk_fp8_f32 v99, v15, v100 op_sel:[0,0,1]
	v_mov_b32_e32 v100, v0
	v_cvt_pk_fp8_f32 v101, v102, v103
	v_mov_b32_e32 v102, v0
	v_mov_b32_e32 v103, v0
	v_exp_f32_e32 v108, v110
	v_exp_f32_e32 v109, v111
	v_cvt_pk_fp8_f32 v96, v112, v113
	v_cvt_pk_fp8_f32 v97, v1, v10
	v_cvt_pk_fp8_f32 v98, v116, v117
	v_cvt_pk_fp8_f32 v100, v120, v121
	v_cvt_pk_fp8_f32 v102, v124, v125
	v_cvt_pk_fp8_f32 v103, v106, v107
	v_cvt_pk_fp8_f32 v96, v114, v115 op_sel:[0,0,1]
	v_cvt_pk_fp8_f32 v97, v11, v12 op_sel:[0,0,1]
	v_cvt_pk_fp8_f32 v98, v118, v119 op_sel:[0,0,1]
	v_cvt_pk_fp8_f32 v100, v122, v123 op_sel:[0,0,1]
	v_cvt_pk_fp8_f32 v101, v104, v105 op_sel:[0,0,1]
	v_cvt_pk_fp8_f32 v102, v126, v127 op_sel:[0,0,1]
	v_cvt_pk_fp8_f32 v103, v108, v109 op_sel:[0,0,1]
	s_waitcnt vmcnt(0)
	s_andn2_b64 vcc, exec, s[54:55]
	s_cbranch_vccnz .LBB0_359
	s_ashr_i32 s45, s44, 31
	s_ashr_i32 s47, s46, 31
	s_lshl_b64 s[56:57], s[44:45], 23
	s_lshl_b64 s[58:59], s[44:45], 21
	s_lshr_b32 s45, s83, 2
	s_lshl_b64 s[54:55], s[46:47], 18
	s_lshl_b32 s36, s83, 7
	s_lshl_b32 s47, s45, 7
	s_add_u32 s53, s63, s54
	s_addc_u32 s54, s64, s55
	s_add_u32 s53, s53, s56
	s_addc_u32 s55, s54, s57
	s_add_u32 s54, s53, s36
	s_addc_u32 s55, s55, 0
	s_add_u32 s36, s65, s58
	s_addc_u32 s53, s66, s59
	s_add_u32 s56, s36, s47
	s_addc_u32 s57, s53, 0
	s_lshl_b32 s36, s44, 1
	v_lshl_add_u64 v[10:11], s[54:55], 0, v[208:209]
	s_or_b32 s58, s36, s45
	v_lshl_add_u64 v[10:11], v[10:11], 0, v[210:211]
	s_ashr_i32 s59, s58, 31
	global_load_dwordx4 v[176:179], v[10:11], off
	global_load_dwordx4 v[180:183], v[10:11], off offset:16
	global_load_dwordx4 v[184:187], v[10:11], off offset:64
	global_load_dwordx4 v[188:191], v[10:11], off offset:80
	v_lshl_add_u64 v[10:11], s[56:57], 0, v[202:203]
	s_mov_b32 m0, s70
	s_lshl_b64 s[58:59], s[58:59], 20
	v_lshl_add_u64 v[10:11], v[10:11], 0, v[204:205]
	v_lshl_add_u64 v[12:13], v[206:207], 0, s[58:59]
	global_load_lds_dwordx4 v[10:11], off
	s_mov_b32 m0, s68
	v_lshl_add_u64 v[10:11], v[10:11], 0, s[38:39]
	global_load_lds_dwordx4 v[12:13], off
	s_mov_b32 m0, s72
	s_nop 0
	global_load_lds_dwordx4 v[10:11], off
	v_lshl_add_u64 v[10:11], v[12:13], 0, s[40:41]
	s_mov_b32 m0, s74
	s_nop 0
	global_load_lds_dwordx4 v[10:11], off
	s_branch .LBB0_359
